# grid-barrier spin loops poll with s_sleep 0 instead of s_sleep 1
# baseline (speedup 1.0000x reference)
; __global__ void __launch_bounds__(NTH) mega(Params p_arg){
;     ...
;     if (rep_a==0x7fffffff) grid.sync();
.LBB0_99:
	s_sleep 0
	global_load_dword v1, v25, s[8:9] offset:32 sc1
	s_waitcnt vmcnt(0)
	v_and_b32_e32 v1, 0xffff0000, v1
	v_cmp_ne_u32_e32 vcc, v1, v0
	s_or_b64 s[10:11], vcc, s[10:11]
	s_andn2_b64 exec, exec, s[10:11]
	s_cbranch_execnz .LBB0_99

; __device__ __forceinline__ unsigned xb_ld(unsigned* p)              { return __hip_atomic_load(p, __ATOMIC_RELAXED, __HIP_MEMORY_SCOPE_AGENT); }
; __device__ __forceinline__ void xcd_barrier_complete(unsigned* bar, unsigned x, unsigned& nloc, unsigned& nx) {
;     ...
;     for (;;) {
;         sum = 0u; cnt = 0u; mine = 0u;
; #pragma unroll
;         for (unsigned j = 0; j < 16; ++j) { const unsigned c = xb_ld(&bar[XB_XCNT(j)]); sum += c; cnt += (c > 0u) ? 1u : 0u; mine = (j == x) ? c : mine; }
;         if (sum == G) break;
;         __builtin_amdgcn_s_sleep(1);
;         if ((++sp & 255u) == 0u) { if (xb_ld(&bar[XB_TMO])) break; if (sp > XB_SPIN_CAP) { atomicAdd(&bar[XB_TMO], 1u); break; } }
;     }
.LBB0_107:
	s_waitcnt lgkmcnt(0)
	v_mov_b64_e32 v[0:1], s[62:63]
	v_mov_b64_e32 v[2:3], s[64:65]
	flat_load_dword v0, v[0:1] sc1
	v_mov_b64_e32 v[4:5], s[68:69]
	flat_load_dword v1, v[2:3] sc1
	v_mov_b64_e32 v[2:3], s[66:67]
	flat_load_dword v2, v[2:3] sc1
	v_mov_b64_e32 v[6:7], s[72:73]
	flat_load_dword v3, v[4:5] sc1
	v_mov_b64_e32 v[4:5], s[70:71]
	flat_load_dword v4, v[4:5] sc1
	v_mov_b64_e32 v[8:9], s[76:77]
	flat_load_dword v5, v[6:7] sc1
	v_mov_b64_e32 v[6:7], s[74:75]
	flat_load_dword v6, v[6:7] sc1
	v_mov_b64_e32 v[10:11], s[80:81]
	flat_load_dword v7, v[8:9] sc1
	v_mov_b64_e32 v[8:9], s[78:79]
	flat_load_dword v8, v[8:9] sc1
	v_mov_b64_e32 v[12:13], s[84:85]
	flat_load_dword v9, v[10:11] sc1
	v_mov_b64_e32 v[10:11], s[82:83]
	flat_load_dword v10, v[10:11] sc1
	v_mov_b64_e32 v[14:15], s[88:89]
	flat_load_dword v11, v[12:13] sc1
	v_mov_b64_e32 v[12:13], s[86:87]
	flat_load_dword v12, v[12:13] sc1
	v_mov_b64_e32 v[16:17], s[92:93]
	flat_load_dword v13, v[14:15] sc1
	v_mov_b64_e32 v[14:15], s[90:91]
	flat_load_dword v14, v[14:15] sc1
	v_readlane_b32 s10, v253, 16
	flat_load_dword v15, v[16:17] sc1
	s_or_b64 s[46:47], s[46:47], exec
	s_or_b64 s[44:45], s[44:45], exec
	s_waitcnt vmcnt(0) lgkmcnt(0)
	v_add_u32_e32 v16, v1, v0
	v_add_u32_e32 v16, v16, v2
	v_add_u32_e32 v16, v16, v3
	v_add_u32_e32 v16, v16, v4
	v_add_u32_e32 v16, v16, v5
	v_add_u32_e32 v16, v16, v6
	v_add_u32_e32 v16, v16, v7
	v_add_u32_e32 v16, v16, v8
	v_add_u32_e32 v16, v16, v9
	v_add_u32_e32 v16, v16, v10
	v_add_u32_e32 v16, v16, v11
	v_add_u32_e32 v16, v16, v12
	v_add_u32_e32 v16, v16, v13
	v_add_u32_e32 v16, v16, v14
	v_add_u32_e32 v16, v16, v15
	v_cmp_ne_u32_e32 vcc, s10, v16
	s_and_saveexec_b64 s[48:49], vcc
	s_cbranch_execz .LBB0_106
	s_and_b32 s10, s52, 0xff
	s_mov_b64 s[50:51], -1
	s_cmp_eq_u32 s10, 0
	s_mov_b64 s[12:13], -1
	s_mov_b64 s[10:11], -1
	s_sleep 0
	s_cbranch_scc1 .LBB0_110
	s_and_saveexec_b64 s[14:15], s[12:13]
	s_cbranch_execz .LBB0_105
	s_branch .LBB0_113

; __device__ __forceinline__ unsigned xb_ld(unsigned* p)              { return __hip_atomic_load(p, __ATOMIC_RELAXED, __HIP_MEMORY_SCOPE_AGENT); }
; __device__ __forceinline__ void xcd_barrier_complete(unsigned* bar, unsigned x, unsigned& nloc, unsigned& nx) {
;     ...
;     for (;;) {
;         sum = 0u; cnt = 0u; mine = 0u;
; #pragma unroll
;         for (unsigned j = 0; j < 16; ++j) { const unsigned c = xb_ld(&bar[XB_XCNT(j)]); sum += c; cnt += (c > 0u) ? 1u : 0u; mine = (j == x) ? c : mine; }
;         if (sum == G) break;
;         __builtin_amdgcn_s_sleep(1);
;         if ((++sp & 255u) == 0u) { if (xb_ld(&bar[XB_TMO])) break; if (sp > XB_SPIN_CAP) { atomicAdd(&bar[XB_TMO], 1u); break; } }
;     }
.LBB0_157:
	flat_load_dword v47, v[0:1] sc1
	flat_load_dword v32, v[2:3] sc1
	flat_load_dword v33, v[4:5] sc1
	flat_load_dword v34, v[6:7] sc1
	flat_load_dword v35, v[8:9] sc1
	flat_load_dword v36, v[10:11] sc1
	flat_load_dword v37, v[12:13] sc1
	flat_load_dword v38, v[14:15] sc1
	flat_load_dword v39, v[16:17] sc1
	flat_load_dword v40, v[18:19] sc1
	flat_load_dword v41, v[20:21] sc1
	flat_load_dword v42, v[22:23] sc1
	flat_load_dword v43, v[24:25] sc1
	flat_load_dword v44, v[26:27] sc1
	flat_load_dword v45, v[28:29] sc1
	flat_load_dword v46, v[30:31] sc1
	s_or_b64 s[10:11], s[10:11], exec
	s_or_b64 s[8:9], s[8:9], exec
	s_waitcnt vmcnt(0) lgkmcnt(0)
	v_add_u32_e32 v48, v32, v47
	v_add_u32_e32 v48, v48, v33
	v_add_u32_e32 v48, v48, v34
	v_add_u32_e32 v48, v48, v35
	v_add_u32_e32 v48, v48, v36
	v_add_u32_e32 v48, v48, v37
	v_add_u32_e32 v48, v48, v38
	v_add_u32_e32 v48, v48, v39
	v_add_u32_e32 v48, v48, v40
	v_add_u32_e32 v48, v48, v41
	v_add_u32_e32 v48, v48, v42
	v_add_u32_e32 v48, v48, v43
	v_add_u32_e32 v48, v48, v44
	v_add_u32_e32 v48, v48, v45
	v_add_u32_e32 v48, v48, v46
	v_cmp_ne_u32_e32 vcc, s22, v48
	s_and_saveexec_b64 s[12:13], vcc
	s_cbranch_execz .LBB0_156
	s_and_b32 s16, s23, 0xff
	s_mov_b64 s[14:15], -1
	s_cmp_eq_u32 s16, 0
	s_mov_b64 s[18:19], -1
	s_mov_b64 s[16:17], -1
	s_sleep 0
	s_cbranch_scc1 .LBB0_160
	s_and_saveexec_b64 s[20:21], s[18:19]
	s_cbranch_execz .LBB0_155
	s_branch .LBB0_163

; __device__ __forceinline__ unsigned xb_ld(unsigned* p)              { return __hip_atomic_load(p, __ATOMIC_RELAXED, __HIP_MEMORY_SCOPE_AGENT); }
; __device__ __forceinline__ void xcd_barrier_complete(unsigned* bar, unsigned x, unsigned& nloc, unsigned& nx) {
;     ...
;     for (;;) {
;         sum = 0u; cnt = 0u; mine = 0u;
; #pragma unroll
;         for (unsigned j = 0; j < 16; ++j) { const unsigned c = xb_ld(&bar[XB_XCNT(j)]); sum += c; cnt += (c > 0u) ? 1u : 0u; mine = (j == x) ? c : mine; }
;         if (sum == G) break;
;         __builtin_amdgcn_s_sleep(1);
;         if ((++sp & 255u) == 0u) { if (xb_ld(&bar[XB_TMO])) break; if (sp > XB_SPIN_CAP) { atomicAdd(&bar[XB_TMO], 1u); break; } }
;     }
.LBB0_598:
	s_waitcnt lgkmcnt(0)
	v_mov_b64_e32 v[0:1], s[58:59]
	v_mov_b64_e32 v[2:3], s[60:61]
	flat_load_dword v0, v[0:1] sc1
	v_readlane_b32 s24, v253, 16
	flat_load_dword v1, v[2:3] sc1
	v_mov_b64_e32 v[2:3], s[62:63]
	flat_load_dword v2, v[2:3] sc1
	s_or_b64 s[42:43], s[42:43], exec
	s_or_b64 s[40:41], s[40:41], exec
	s_waitcnt vmcnt(0) lgkmcnt(0)
	v_add_u32_e32 v4, v1, v0
	v_add_u32_e32 v6, v4, v2
	v_mov_b64_e32 v[4:5], s[64:65]
	flat_load_dword v3, v[4:5] sc1
	v_mov_b64_e32 v[4:5], s[66:67]
	flat_load_dword v4, v[4:5] sc1
	s_waitcnt vmcnt(0) lgkmcnt(0)
	v_add_u32_e32 v6, v6, v3
	v_add_u32_e32 v8, v6, v4
	v_mov_b64_e32 v[6:7], s[68:69]
	flat_load_dword v5, v[6:7] sc1
	v_mov_b64_e32 v[6:7], s[70:71]
	flat_load_dword v6, v[6:7] sc1
	s_waitcnt vmcnt(0) lgkmcnt(0)
	v_add_u32_e32 v8, v8, v5
	v_add_u32_e32 v10, v8, v6
	v_mov_b64_e32 v[8:9], s[72:73]
	flat_load_dword v7, v[8:9] sc1
	v_mov_b64_e32 v[8:9], s[74:75]
	flat_load_dword v8, v[8:9] sc1
	s_waitcnt vmcnt(0) lgkmcnt(0)
	v_add_u32_e32 v10, v10, v7
	v_add_u32_e32 v12, v10, v8
	v_mov_b64_e32 v[10:11], s[76:77]
	flat_load_dword v9, v[10:11] sc1
	v_mov_b64_e32 v[10:11], s[78:79]
	flat_load_dword v10, v[10:11] sc1
	s_waitcnt vmcnt(0) lgkmcnt(0)
	v_add_u32_e32 v12, v12, v9
	v_add_u32_e32 v14, v12, v10
	v_mov_b64_e32 v[12:13], s[80:81]
	flat_load_dword v11, v[12:13] sc1
	v_mov_b64_e32 v[12:13], s[82:83]
	flat_load_dword v12, v[12:13] sc1
	s_waitcnt vmcnt(0) lgkmcnt(0)
	v_add_u32_e32 v14, v14, v11
	v_add_u32_e32 v16, v14, v12
	v_mov_b64_e32 v[14:15], s[84:85]
	flat_load_dword v13, v[14:15] sc1
	v_mov_b64_e32 v[14:15], s[86:87]
	flat_load_dword v14, v[14:15] sc1
	s_waitcnt vmcnt(0) lgkmcnt(0)
	v_add_u32_e32 v16, v16, v13
	v_add_u32_e32 v18, v16, v14
	v_mov_b64_e32 v[16:17], s[88:89]
	flat_load_dword v15, v[16:17] sc1
	s_waitcnt vmcnt(0) lgkmcnt(0)
	v_add_u32_e32 v16, v18, v15
	v_cmp_ne_u32_e32 vcc, s24, v16
	s_and_saveexec_b64 s[44:45], vcc
	s_cbranch_execz .LBB0_597
	s_and_b32 s24, s33, 0xff
	s_mov_b64 s[46:47], -1
	s_cmp_eq_u32 s24, 0
	s_mov_b64 s[50:51], -1
	s_mov_b64 s[48:49], -1
	s_sleep 0
	s_cbranch_scc1 .LBB0_601
	s_and_saveexec_b64 s[24:25], s[50:51]
	s_cbranch_execz .LBB0_596
	s_branch .LBB0_604

; __device__ __forceinline__ unsigned xb_ld(unsigned* p)              { return __hip_atomic_load(p, __ATOMIC_RELAXED, __HIP_MEMORY_SCOPE_AGENT); }
; __device__ __forceinline__ void xcd_barrier_complete(unsigned* bar, unsigned x, unsigned& nloc, unsigned& nx) {
;     ...
;     for (;;) {
;         sum = 0u; cnt = 0u; mine = 0u;
; #pragma unroll
;         for (unsigned j = 0; j < 16; ++j) { const unsigned c = xb_ld(&bar[XB_XCNT(j)]); sum += c; cnt += (c > 0u) ? 1u : 0u; mine = (j == x) ? c : mine; }
;         if (sum == G) break;
;         __builtin_amdgcn_s_sleep(1);
;         if ((++sp & 255u) == 0u) { if (xb_ld(&bar[XB_TMO])) break; if (sp > XB_SPIN_CAP) { atomicAdd(&bar[XB_TMO], 1u); break; } }
;     }
.LBB0_1145:
	v_readlane_b32 s12, v253, 50
	v_readlane_b32 s13, v253, 51
	s_or_b64 s[40:41], s[40:41], exec
	s_or_b64 s[38:39], s[38:39], exec
	s_waitcnt lgkmcnt(0)
	v_mov_b64_e32 v[0:1], s[12:13]
	v_readlane_b32 s12, v253, 52
	v_readlane_b32 s13, v253, 53
	flat_load_dword v0, v[0:1] sc1
	s_nop 0
	v_mov_b64_e32 v[2:3], s[12:13]
	v_readlane_b32 s12, v253, 54
	v_readlane_b32 s13, v253, 55
	flat_load_dword v1, v[2:3] sc1
	s_waitcnt vmcnt(0) lgkmcnt(0)
	v_add_u32_e32 v4, v1, v0
	v_mov_b64_e32 v[2:3], s[12:13]
	flat_load_dword v2, v[2:3] sc1
	v_readlane_b32 s12, v253, 56
	v_readlane_b32 s13, v253, 57
	s_waitcnt vmcnt(0) lgkmcnt(0)
	v_add_u32_e32 v6, v4, v2
	v_mov_b64_e32 v[4:5], s[12:13]
	v_readlane_b32 s12, v253, 58
	v_readlane_b32 s13, v253, 59
	flat_load_dword v3, v[4:5] sc1
	s_waitcnt vmcnt(0) lgkmcnt(0)
	v_add_u32_e32 v6, v6, v3
	v_mov_b64_e32 v[4:5], s[12:13]
	flat_load_dword v4, v[4:5] sc1
	v_readlane_b32 s12, v253, 60
	v_readlane_b32 s13, v253, 61
	s_waitcnt vmcnt(0) lgkmcnt(0)
	v_add_u32_e32 v8, v6, v4
	v_mov_b64_e32 v[6:7], s[12:13]
	v_readlane_b32 s12, v253, 62
	v_readlane_b32 s13, v253, 63
	flat_load_dword v5, v[6:7] sc1
	s_waitcnt vmcnt(0) lgkmcnt(0)
	v_add_u32_e32 v8, v8, v5
	v_mov_b64_e32 v[6:7], s[12:13]
	flat_load_dword v6, v[6:7] sc1
	v_readlane_b32 s12, v254, 0
	v_readlane_b32 s13, v254, 1
	s_waitcnt vmcnt(0) lgkmcnt(0)
	v_add_u32_e32 v10, v8, v6
	v_mov_b64_e32 v[8:9], s[12:13]
	v_readlane_b32 s12, v254, 2
	v_readlane_b32 s13, v254, 3
	flat_load_dword v7, v[8:9] sc1
	s_waitcnt vmcnt(0) lgkmcnt(0)
	v_add_u32_e32 v10, v10, v7
	v_mov_b64_e32 v[8:9], s[12:13]
	flat_load_dword v8, v[8:9] sc1
	v_readlane_b32 s12, v254, 4
	v_readlane_b32 s13, v254, 5
	s_waitcnt vmcnt(0) lgkmcnt(0)
	v_add_u32_e32 v12, v10, v8
	v_mov_b64_e32 v[10:11], s[12:13]
	v_readlane_b32 s12, v254, 6
	v_readlane_b32 s13, v254, 7
	flat_load_dword v9, v[10:11] sc1
	s_waitcnt vmcnt(0) lgkmcnt(0)
	v_add_u32_e32 v12, v12, v9
	v_mov_b64_e32 v[10:11], s[12:13]
	flat_load_dword v10, v[10:11] sc1
	v_readlane_b32 s12, v254, 8
	v_readlane_b32 s13, v254, 9
	s_waitcnt vmcnt(0) lgkmcnt(0)
	v_add_u32_e32 v14, v12, v10
	v_mov_b64_e32 v[12:13], s[12:13]
	v_readlane_b32 s12, v254, 10
	v_readlane_b32 s13, v254, 11
	flat_load_dword v11, v[12:13] sc1
	s_waitcnt vmcnt(0) lgkmcnt(0)
	v_add_u32_e32 v14, v14, v11
	v_mov_b64_e32 v[12:13], s[12:13]
	flat_load_dword v12, v[12:13] sc1
	v_readlane_b32 s12, v254, 12
	v_readlane_b32 s13, v254, 13
	s_waitcnt vmcnt(0) lgkmcnt(0)
	v_add_u32_e32 v16, v14, v12
	v_mov_b64_e32 v[14:15], s[12:13]
	v_readlane_b32 s12, v254, 14
	v_readlane_b32 s13, v254, 15
	flat_load_dword v13, v[14:15] sc1
	s_waitcnt vmcnt(0) lgkmcnt(0)
	v_add_u32_e32 v16, v16, v13
	v_mov_b64_e32 v[14:15], s[12:13]
	flat_load_dword v14, v[14:15] sc1
	v_readlane_b32 s12, v254, 16
	v_readlane_b32 s13, v254, 17
	s_waitcnt vmcnt(0) lgkmcnt(0)
	v_add_u32_e32 v18, v16, v14
	v_mov_b64_e32 v[16:17], s[12:13]
	flat_load_dword v15, v[16:17] sc1
	v_readlane_b32 s12, v253, 16
	s_waitcnt vmcnt(0) lgkmcnt(0)
	v_add_u32_e32 v16, v18, v15
	v_cmp_ne_u32_e32 vcc, s12, v16
	s_and_saveexec_b64 s[42:43], vcc
	s_cbranch_execz .LBB0_1144
	s_and_b32 s19, s18, 0xff
	s_mov_b64 s[12:13], -1
	s_cmp_eq_u32 s19, 0
	s_mov_b64 s[46:47], -1
	s_mov_b64 s[44:45], -1
	s_sleep 0
	s_cbranch_scc1 .LBB0_1148
	s_and_saveexec_b64 s[48:49], s[46:47]
	s_cbranch_execz .LBB0_1143
	s_branch .LBB0_1151

; __device__ __forceinline__ unsigned xb_ld(unsigned* p)              { return __hip_atomic_load(p, __ATOMIC_RELAXED, __HIP_MEMORY_SCOPE_AGENT); }
; __device__ __forceinline__ void xcd_barrier_complete(unsigned* bar, unsigned x, unsigned& nloc, unsigned& nx) {
;     ...
;     for (;;) {
;         sum = 0u; cnt = 0u; mine = 0u;
; #pragma unroll
;         for (unsigned j = 0; j < 16; ++j) { const unsigned c = xb_ld(&bar[XB_XCNT(j)]); sum += c; cnt += (c > 0u) ? 1u : 0u; mine = (j == x) ? c : mine; }
;         if (sum == G) break;
;         __builtin_amdgcn_s_sleep(1);
;         if ((++sp & 255u) == 0u) { if (xb_ld(&bar[XB_TMO])) break; if (sp > XB_SPIN_CAP) { atomicAdd(&bar[XB_TMO], 1u); break; } }
;     }
.LBB0_1354:
	v_readlane_b32 s12, v253, 50
	v_readlane_b32 s13, v253, 51
	s_or_b64 s[38:39], s[38:39], exec
	s_or_b64 s[36:37], s[36:37], exec
	s_waitcnt lgkmcnt(0)
	v_mov_b64_e32 v[0:1], s[12:13]
	v_readlane_b32 s12, v253, 52
	v_readlane_b32 s13, v253, 53
	flat_load_dword v0, v[0:1] sc1
	s_nop 0
	v_mov_b64_e32 v[2:3], s[12:13]
	v_readlane_b32 s12, v253, 54
	v_readlane_b32 s13, v253, 55
	flat_load_dword v1, v[2:3] sc1
	s_waitcnt vmcnt(0) lgkmcnt(0)
	v_add_u32_e32 v4, v1, v0
	v_mov_b64_e32 v[2:3], s[12:13]
	flat_load_dword v2, v[2:3] sc1
	v_readlane_b32 s12, v253, 56
	v_readlane_b32 s13, v253, 57
	s_waitcnt vmcnt(0) lgkmcnt(0)
	v_add_u32_e32 v6, v4, v2
	v_mov_b64_e32 v[4:5], s[12:13]
	v_readlane_b32 s12, v253, 58
	v_readlane_b32 s13, v253, 59
	flat_load_dword v3, v[4:5] sc1
	s_waitcnt vmcnt(0) lgkmcnt(0)
	v_add_u32_e32 v6, v6, v3
	v_mov_b64_e32 v[4:5], s[12:13]
	flat_load_dword v4, v[4:5] sc1
	v_readlane_b32 s12, v253, 60
	v_readlane_b32 s13, v253, 61
	s_waitcnt vmcnt(0) lgkmcnt(0)
	v_add_u32_e32 v8, v6, v4
	v_mov_b64_e32 v[6:7], s[12:13]
	v_readlane_b32 s12, v253, 62
	v_readlane_b32 s13, v253, 63
	flat_load_dword v5, v[6:7] sc1
	s_waitcnt vmcnt(0) lgkmcnt(0)
	v_add_u32_e32 v8, v8, v5
	v_mov_b64_e32 v[6:7], s[12:13]
	flat_load_dword v6, v[6:7] sc1
	v_readlane_b32 s12, v254, 0
	v_readlane_b32 s13, v254, 1
	s_waitcnt vmcnt(0) lgkmcnt(0)
	v_add_u32_e32 v10, v8, v6
	v_mov_b64_e32 v[8:9], s[12:13]
	v_readlane_b32 s12, v254, 2
	v_readlane_b32 s13, v254, 3
	flat_load_dword v7, v[8:9] sc1
	s_waitcnt vmcnt(0) lgkmcnt(0)
	v_add_u32_e32 v10, v10, v7
	v_mov_b64_e32 v[8:9], s[12:13]
	flat_load_dword v8, v[8:9] sc1
	v_readlane_b32 s12, v254, 4
	v_readlane_b32 s13, v254, 5
	s_waitcnt vmcnt(0) lgkmcnt(0)
	v_add_u32_e32 v12, v10, v8
	v_mov_b64_e32 v[10:11], s[12:13]
	v_readlane_b32 s12, v254, 6
	v_readlane_b32 s13, v254, 7
	flat_load_dword v9, v[10:11] sc1
	s_waitcnt vmcnt(0) lgkmcnt(0)
	v_add_u32_e32 v12, v12, v9
	v_mov_b64_e32 v[10:11], s[12:13]
	flat_load_dword v10, v[10:11] sc1
	v_readlane_b32 s12, v254, 8
	v_readlane_b32 s13, v254, 9
	s_waitcnt vmcnt(0) lgkmcnt(0)
	v_add_u32_e32 v14, v12, v10
	v_mov_b64_e32 v[12:13], s[12:13]
	v_readlane_b32 s12, v254, 10
	v_readlane_b32 s13, v254, 11
	flat_load_dword v11, v[12:13] sc1
	s_waitcnt vmcnt(0) lgkmcnt(0)
	v_add_u32_e32 v14, v14, v11
	v_mov_b64_e32 v[12:13], s[12:13]
	flat_load_dword v12, v[12:13] sc1
	v_readlane_b32 s12, v254, 12
	v_readlane_b32 s13, v254, 13
	s_waitcnt vmcnt(0) lgkmcnt(0)
	v_add_u32_e32 v16, v14, v12
	v_mov_b64_e32 v[14:15], s[12:13]
	v_readlane_b32 s12, v254, 14
	v_readlane_b32 s13, v254, 15
	flat_load_dword v13, v[14:15] sc1
	s_waitcnt vmcnt(0) lgkmcnt(0)
	v_add_u32_e32 v16, v16, v13
	v_mov_b64_e32 v[14:15], s[12:13]
	flat_load_dword v14, v[14:15] sc1
	v_readlane_b32 s12, v254, 16
	v_readlane_b32 s13, v254, 17
	s_waitcnt vmcnt(0) lgkmcnt(0)
	v_add_u32_e32 v18, v16, v14
	v_mov_b64_e32 v[16:17], s[12:13]
	flat_load_dword v15, v[16:17] sc1
	v_readlane_b32 s12, v253, 16
	s_waitcnt vmcnt(0) lgkmcnt(0)
	v_add_u32_e32 v16, v18, v15
	v_cmp_ne_u32_e32 vcc, s12, v16
	s_and_saveexec_b64 s[40:41], vcc
	s_cbranch_execz .LBB0_1353
	s_and_b32 s19, s18, 0xff
	s_mov_b64 s[12:13], -1
	s_cmp_eq_u32 s19, 0
	s_mov_b64 s[44:45], -1
	s_mov_b64 s[42:43], -1
	s_sleep 0
	s_cbranch_scc1 .LBB0_1357
	s_and_saveexec_b64 s[46:47], s[44:45]
	s_cbranch_execz .LBB0_1352
	s_branch .LBB0_1360

; __device__ __forceinline__ unsigned xb_ld(unsigned* p)              { return __hip_atomic_load(p, __ATOMIC_RELAXED, __HIP_MEMORY_SCOPE_AGENT); }
; __device__ __forceinline__ void xcd_barrier_complete(unsigned* bar, unsigned x, unsigned& nloc, unsigned& nx) {
;     ...
;     for (;;) {
;         sum = 0u; cnt = 0u; mine = 0u;
; #pragma unroll
;         for (unsigned j = 0; j < 16; ++j) { const unsigned c = xb_ld(&bar[XB_XCNT(j)]); sum += c; cnt += (c > 0u) ? 1u : 0u; mine = (j == x) ? c : mine; }
;         if (sum == G) break;
;         __builtin_amdgcn_s_sleep(1);
;         if ((++sp & 255u) == 0u) { if (xb_ld(&bar[XB_TMO])) break; if (sp > XB_SPIN_CAP) { atomicAdd(&bar[XB_TMO], 1u); break; } }
;     }
.LBB0_1400:
	flat_load_dword v47, v[0:1] sc1
	flat_load_dword v32, v[2:3] sc1
	flat_load_dword v33, v[4:5] sc1
	flat_load_dword v34, v[6:7] sc1
	flat_load_dword v35, v[8:9] sc1
	flat_load_dword v36, v[10:11] sc1
	flat_load_dword v37, v[12:13] sc1
	flat_load_dword v38, v[14:15] sc1
	flat_load_dword v39, v[16:17] sc1
	flat_load_dword v40, v[18:19] sc1
	flat_load_dword v41, v[20:21] sc1
	flat_load_dword v42, v[22:23] sc1
	flat_load_dword v43, v[24:25] sc1
	flat_load_dword v44, v[26:27] sc1
	flat_load_dword v45, v[28:29] sc1
	flat_load_dword v46, v[30:31] sc1
	v_readlane_b32 s10, v253, 16
	s_or_b64 s[8:9], s[8:9], exec
	s_or_b64 s[6:7], s[6:7], exec
	s_waitcnt vmcnt(0) lgkmcnt(0)
	v_add_u32_e32 v48, v32, v47
	v_add_u32_e32 v48, v48, v33
	v_add_u32_e32 v48, v48, v34
	v_add_u32_e32 v48, v48, v35
	v_add_u32_e32 v48, v48, v36
	v_add_u32_e32 v48, v48, v37
	v_add_u32_e32 v48, v48, v38
	v_add_u32_e32 v48, v48, v39
	v_add_u32_e32 v48, v48, v40
	v_add_u32_e32 v48, v48, v41
	v_add_u32_e32 v48, v48, v42
	v_add_u32_e32 v48, v48, v43
	v_add_u32_e32 v48, v48, v44
	v_add_u32_e32 v48, v48, v45
	v_add_u32_e32 v48, v48, v46
	v_cmp_ne_u32_e32 vcc, s10, v48
	s_and_saveexec_b64 s[10:11], vcc
	s_cbranch_execz .LBB0_1399
	s_and_b32 s14, s20, 0xff
	s_mov_b64 s[12:13], -1
	s_cmp_eq_u32 s14, 0
	s_mov_b64 s[16:17], -1
	s_mov_b64 s[14:15], -1
	s_sleep 0
	s_cbranch_scc1 .LBB0_1403
	s_and_saveexec_b64 s[18:19], s[16:17]
	s_cbranch_execz .LBB0_1398
	s_branch .LBB0_1406

; __device__ __forceinline__ unsigned xb_ld(unsigned* p)              { return __hip_atomic_load(p, __ATOMIC_RELAXED, __HIP_MEMORY_SCOPE_AGENT); }
; __device__ __forceinline__ void xcd_barrier_complete(unsigned* bar, unsigned x, unsigned& nloc, unsigned& nx) {
;     ...
;     for (;;) {
;         sum = 0u; cnt = 0u; mine = 0u;
; #pragma unroll
;         for (unsigned j = 0; j < 16; ++j) { const unsigned c = xb_ld(&bar[XB_XCNT(j)]); sum += c; cnt += (c > 0u) ? 1u : 0u; mine = (j == x) ? c : mine; }
;         if (sum == G) break;
;         __builtin_amdgcn_s_sleep(1);
;         if ((++sp & 255u) == 0u) { if (xb_ld(&bar[XB_TMO])) break; if (sp > XB_SPIN_CAP) { atomicAdd(&bar[XB_TMO], 1u); break; } }
;     }
.LBB0_1461:
	flat_load_dword v47, v[0:1] sc1
	flat_load_dword v32, v[2:3] sc1
	flat_load_dword v33, v[4:5] sc1
	flat_load_dword v34, v[6:7] sc1
	flat_load_dword v35, v[8:9] sc1
	flat_load_dword v36, v[10:11] sc1
	flat_load_dword v37, v[12:13] sc1
	flat_load_dword v38, v[14:15] sc1
	flat_load_dword v39, v[16:17] sc1
	flat_load_dword v40, v[18:19] sc1
	flat_load_dword v41, v[20:21] sc1
	flat_load_dword v42, v[22:23] sc1
	flat_load_dword v43, v[24:25] sc1
	flat_load_dword v44, v[26:27] sc1
	flat_load_dword v45, v[28:29] sc1
	flat_load_dword v46, v[30:31] sc1
	v_readlane_b32 s12, v253, 16
	s_or_b64 s[10:11], s[10:11], exec
	s_or_b64 s[8:9], s[8:9], exec
	s_waitcnt vmcnt(0) lgkmcnt(0)
	v_add_u32_e32 v48, v32, v47
	v_add_u32_e32 v48, v48, v33
	v_add_u32_e32 v48, v48, v34
	v_add_u32_e32 v48, v48, v35
	v_add_u32_e32 v48, v48, v36
	v_add_u32_e32 v48, v48, v37
	v_add_u32_e32 v48, v48, v38
	v_add_u32_e32 v48, v48, v39
	v_add_u32_e32 v48, v48, v40
	v_add_u32_e32 v48, v48, v41
	v_add_u32_e32 v48, v48, v42
	v_add_u32_e32 v48, v48, v43
	v_add_u32_e32 v48, v48, v44
	v_add_u32_e32 v48, v48, v45
	v_add_u32_e32 v48, v48, v46
	v_cmp_ne_u32_e32 vcc, s12, v48
	s_and_saveexec_b64 s[12:13], vcc
	s_cbranch_execz .LBB0_1460
	s_and_b32 s16, s22, 0xff
	s_mov_b64 s[14:15], -1
	s_cmp_eq_u32 s16, 0
	s_mov_b64 s[18:19], -1
	s_mov_b64 s[16:17], -1
	s_sleep 0
	s_cbranch_scc1 .LBB0_1464
	s_and_saveexec_b64 s[20:21], s[18:19]
	s_cbranch_execz .LBB0_1459
	s_branch .LBB0_1467
